# MLA: MFMA block reorder + softmax row-sum of a tile deferred into the next MFMA block's P.V shadow (sum adds leave the softmax block), on top of the DA pipelined + MFMA row-sum loop
# baseline (speedup 1.0000x reference)
.LBB0_665:
	v_add_f32_e32 v151, v18, v19
	v_lshlrev_b32_e32 v18, 1, v50
	v_and_b32_e32 v18, 32, v18
	v_and_or_b32 v18, v51, s67, v18
	v_and_b32_e32 v19, 0x100, v52
	v_fmac_f32_e32 v151, 0, v58
	v_or3_b32 v158, v18, v19, v53
	v_add_u32_e32 v187, v57, v56
	v_add_u32_e32 v188, 0, v56
	v_cmp_gt_u32_e64 s[4:5], 32, v50
	v_lshl_add_u32 v157, v54, 2, s18
	v_lshlrev_b32_e32 v156, 4, v55
	v_mov_b64_e32 v[32:33], v[16:17]
	v_mov_b64_e32 v[48:49], v[16:17]
	v_mov_b64_e32 v[64:65], v[16:17]
	s_mov_b32 s93, 1
	v_add_u32_e32 v185, s35, v158
	s_mov_b32 s95, 0x8000
	s_movk_i32 s94, 0x4000
	s_mov_b32 s8, 0
	v_mov_b64_e32 v[30:31], v[14:15]
	v_mov_b64_e32 v[28:29], v[12:13]
	v_mov_b64_e32 v[26:27], v[10:11]
	v_mov_b64_e32 v[24:25], v[8:9]
	v_mov_b64_e32 v[22:23], v[6:7]
	v_mov_b64_e32 v[20:21], v[4:5]
	v_mov_b64_e32 v[18:19], v[2:3]
	v_mov_b64_e32 v[46:47], v[14:15]
	v_mov_b64_e32 v[44:45], v[12:13]
	v_mov_b64_e32 v[42:43], v[10:11]
	v_mov_b64_e32 v[40:41], v[8:9]
	v_mov_b64_e32 v[38:39], v[6:7]
	v_mov_b64_e32 v[36:37], v[4:5]
	v_mov_b64_e32 v[34:35], v[2:3]
	v_mov_b64_e32 v[62:63], v[14:15]
	v_mov_b64_e32 v[60:61], v[12:13]
	v_mov_b64_e32 v[58:59], v[10:11]
	v_mov_b64_e32 v[56:57], v[8:9]
	v_mov_b64_e32 v[54:55], v[6:7]
	v_mov_b64_e32 v[52:53], v[4:5]
	v_mov_b64_e32 v[50:51], v[2:3]
	v_add_u32_e32 v189, v187, v160
	v_add_u32_e32 v190, v187, v162
	v_add_u32_e32 v191, v187, v164
	v_add_u32_e32 v192, v187, v166
	v_mov_b32_e32 v255, 1.0
	v_mov_b32_e32 v66, 0
	v_mov_b32_e32 v67, 0
	v_mov_b32_e32 v68, 0
	v_mov_b32_e32 v69, 0
	v_mov_b32_e32 v70, 0
	v_mov_b32_e32 v71, 0
	v_mov_b32_e32 v72, 0
	v_mov_b32_e32 v73, 0
	v_mov_b32_e32 v74, 0
	v_mov_b32_e32 v75, 0
	v_mov_b32_e32 v76, 0
	v_mov_b32_e32 v77, 0
	v_mov_b32_e32 v78, 0
	v_mov_b32_e32 v79, 0
	v_mov_b32_e32 v80, 0
	v_mov_b32_e32 v81, 0
	v_mov_b32_e32 v82, 0
	v_mov_b32_e32 v83, 0
	v_mov_b32_e32 v84, 0
	v_mov_b32_e32 v85, 0
	v_mov_b32_e32 v86, 0
	v_mov_b32_e32 v87, 0
	v_mov_b32_e32 v88, 0
	v_mov_b32_e32 v89, 0
	v_mov_b32_e32 v90, 0
	v_mov_b32_e32 v91, 0
	v_mov_b32_e32 v92, 0
	v_mov_b32_e32 v93, 0
	v_mov_b32_e32 v94, 0
	v_mov_b32_e32 v95, 0
	v_mov_b32_e32 v96, 0
	v_mov_b32_e32 v97, 0
.LBB0_666:
	s_barrier
	s_setprio 3
	s_mov_b32 s12, s94
	s_mov_b32 s94, s8
	v_add_u32_e32 v250, s94, v185
	ds_read_b64_tr_b16 v[202:203], v250 offset:0
	ds_read_b64_tr_b16 v[204:205], v250 offset:0x800
	ds_read_b64_tr_b16 v[206:207], v250 offset:0x1000
	ds_read_b64_tr_b16 v[208:209], v250 offset:0x1800
	ds_read_b64_tr_b16 v[210:211], v250 offset:0x2000
	ds_read_b64_tr_b16 v[212:213], v250 offset:0x2800
	ds_read_b64_tr_b16 v[214:215], v250 offset:0x3000
	ds_read_b64_tr_b16 v[216:217], v250 offset:0x3800
	s_waitcnt lgkmcnt(6)
	v_mfma_f32_32x32x16_bf16 v[50:65], v[130:133], v[202:205], v[50:65]
	v_add_f32_e32 v254, v66, v67
	v_add_f32_e32 v254, v68, v254
	v_add_f32_e32 v254, v69, v254
	ds_read_b64_tr_b16 v[218:219], v250 offset:0x200
	ds_read_b64_tr_b16 v[220:221], v250 offset:0xa00
	s_waitcnt lgkmcnt(6)
	v_mfma_f32_32x32x16_bf16 v[50:65], v[126:129], v[206:209], v[50:65]
	v_add_f32_e32 v254, v70, v254
	v_add_f32_e32 v254, v71, v254
	v_add_f32_e32 v254, v72, v254
	ds_read_b64_tr_b16 v[222:223], v250 offset:0x1200
	ds_read_b64_tr_b16 v[224:225], v250 offset:0x1a00
	ds_read_b128 v[194:197], v190 offset:16384
	s_waitcnt lgkmcnt(7)
	v_mfma_f32_32x32x16_bf16 v[50:65], v[122:125], v[210:213], v[50:65]
	v_add_f32_e32 v254, v73, v254
	v_add_f32_e32 v254, v74, v254
	v_add_f32_e32 v254, v75, v254
	ds_read_b128 v[66:69], v189 offset:16384
	ds_read_b128 v[70:73], v189 offset:24576
	ds_read_b64_tr_b16 v[226:227], v250 offset:0x2200
	ds_read_b64_tr_b16 v[228:229], v250 offset:0x2a00
	s_waitcnt lgkmcnt(9)
	v_mfma_f32_32x32x16_bf16 v[50:65], v[118:121], v[214:217], v[50:65]
	v_add_f32_e32 v254, v76, v254
	v_add_f32_e32 v254, v77, v254
	v_add_f32_e32 v254, v78, v254
	ds_read_b64_tr_b16 v[230:231], v250 offset:0x3200
	ds_read_b64_tr_b16 v[232:233], v250 offset:0x3a00
	ds_read_b128 v[198:201], v190 offset:24576
	s_waitcnt lgkmcnt(10)
	v_mfma_f32_32x32x16_bf16 v[34:49], v[130:133], v[218:221], v[34:49]
	v_add_f32_e32 v254, v79, v254
	v_add_f32_e32 v254, v80, v254
	v_add_f32_e32 v254, v81, v254
	ds_read_b64_tr_b16 v[202:203], v250 offset:0x400
	ds_read_b64_tr_b16 v[204:205], v250 offset:0xc00
	s_waitcnt lgkmcnt(10)
	v_mfma_f32_32x32x16_bf16 v[34:49], v[126:129], v[222:225], v[34:49]
	v_add_f32_e32 v254, v82, v254
	v_add_f32_e32 v254, v83, v254
	v_add_f32_e32 v254, v84, v254
	ds_read_b64_tr_b16 v[206:207], v250 offset:0x1400
	ds_read_b64_tr_b16 v[208:209], v250 offset:0x1c00
	ds_read_b128 v[234:237], v191 offset:16384
	s_waitcnt lgkmcnt(8)
	v_mfma_f32_32x32x16_bf16 v[34:49], v[122:125], v[226:229], v[34:49]
	v_add_f32_e32 v254, v85, v254
	v_add_f32_e32 v254, v86, v254
	v_add_f32_e32 v254, v87, v254
	ds_read_b64_tr_b16 v[210:211], v250 offset:0x2400
	ds_read_b64_tr_b16 v[212:213], v250 offset:0x2c00
	s_waitcnt lgkmcnt(8)
	v_mfma_f32_32x32x16_bf16 v[34:49], v[118:121], v[230:233], v[34:49]
	v_add_f32_e32 v254, v88, v254
	v_add_f32_e32 v254, v89, v254
	v_add_f32_e32 v254, v90, v254
	ds_read_b64_tr_b16 v[214:215], v250 offset:0x3400
	ds_read_b64_tr_b16 v[216:217], v250 offset:0x3c00
	ds_read_b128 v[238:241], v191 offset:24576
	s_waitcnt lgkmcnt(8)
	v_mfma_f32_32x32x16_bf16 v[18:33], v[130:133], v[202:205], v[18:33]
	v_add_f32_e32 v254, v91, v254
	v_add_f32_e32 v254, v92, v254
	v_add_f32_e32 v254, v93, v254
	ds_read_b64_tr_b16 v[218:219], v250 offset:0x600
	ds_read_b64_tr_b16 v[220:221], v250 offset:0xe00
	s_waitcnt lgkmcnt(8)
	v_mfma_f32_32x32x16_bf16 v[18:33], v[126:129], v[206:209], v[18:33]
	v_add_f32_e32 v254, v94, v254
	v_add_f32_e32 v254, v95, v254
	v_add_f32_e32 v254, v96, v254
	ds_read_b64_tr_b16 v[222:223], v250 offset:0x1600
	ds_read_b64_tr_b16 v[224:225], v250 offset:0x1e00
	ds_read_b128 v[242:245], v192 offset:16384
	s_waitcnt lgkmcnt(8)
	v_mfma_f32_32x32x16_bf16 v[18:33], v[122:125], v[210:213], v[18:33]
	v_add_f32_e32 v254, v97, v254
	v_mov_b32_e32 v97, v254
	s_nop 1
	ds_read_b64_tr_b16 v[226:227], v250 offset:0x2600
	ds_read_b64_tr_b16 v[228:229], v250 offset:0x2e00
	s_waitcnt lgkmcnt(8)
	v_mfma_f32_32x32x16_bf16 v[18:33], v[118:121], v[214:217], v[18:33]
	v_permlane32_swap_b32_e32 v254, v97
	v_add_f32_e32 v254, v254, v97
	v_fma_f32 v151, v151, v255, v254
	ds_read_b64_tr_b16 v[230:231], v250 offset:0x3600
	ds_read_b64_tr_b16 v[232:233], v250 offset:0x3e00
	ds_read_b128 v[246:249], v192 offset:24576
	s_waitcnt lgkmcnt(8)
	v_mfma_f32_32x32x16_bf16 v[2:17], v[130:133], v[218:221], v[2:17]
	s_waitcnt lgkmcnt(6)
	v_mfma_f32_32x32x16_bf16 v[2:17], v[126:129], v[222:225], v[2:17]
	v_add_u32_e32 v202, v187, v168
	ds_read_b128 v[202:205], v202 offset:16384
	v_add_u32_e32 v206, v187, v168
	ds_read_b128 v[206:209], v206 offset:24576
	s_waitcnt lgkmcnt(5)
	v_mfma_f32_32x32x16_bf16 v[2:17], v[122:125], v[226:229], v[2:17]
	s_waitcnt lgkmcnt(3)
	v_mfma_f32_32x32x16_bf16 v[2:17], v[118:121], v[230:233], v[2:17]
	v_add_u32_e32 v210, v187, v170
	ds_read_b128 v[210:213], v210 offset:16384
	v_add_u32_e32 v214, v187, v170
	ds_read_b128 v[214:217], v214 offset:24576
	v_mfma_f32_32x32x16_bf16 v[82:97], v[66:69], v[114:117], 0
	v_mfma_f32_32x32x16_bf16 v[66:81], v[70:73], v[114:117], 0
	ds_read_b128 v[218:221], v159
	v_add_u32_e32 v222, v187, v172
	ds_read_b128 v[222:225], v222 offset:16384
	v_add_u32_e32 v226, v187, v172
	ds_read_b128 v[226:229], v226 offset:24576
	v_mfma_f32_32x32x16_bf16 v[82:97], v[194:197], v[110:113], v[82:97]
	v_mfma_f32_32x32x16_bf16 v[66:81], v[198:201], v[110:113], v[66:81]
	ds_read_b128 v[230:233], v159 offset:1024
	v_add_u32_e32 v194, v187, v174
	ds_read_b128 v[194:197], v194 offset:16384
	v_add_u32_e32 v198, v187, v174
	ds_read_b128 v[198:201], v198 offset:24576
	v_mfma_f32_32x32x16_bf16 v[82:97], v[234:237], v[106:109], v[82:97]
	v_mfma_f32_32x32x16_bf16 v[66:81], v[238:241], v[106:109], v[66:81]
	ds_read_b128 v[234:237], v159 offset:2048
	v_add_u32_e32 v238, v188, v177
	ds_read_b128 v[238:241], v238 offset:40960
	v_mfma_f32_32x32x16_bf16 v[82:97], v[242:245], v[102:105], v[82:97]
	s_waitcnt lgkmcnt(12)
	v_mfma_f32_32x32x16_bf16 v[66:81], v[246:249], v[102:105], v[66:81]
	v_add_u32_e32 v242, v188, v177
	ds_read_b128 v[242:245], v242 offset:45056
	ds_read_b128 v[246:249], v159 offset:3072
	s_waitcnt lgkmcnt(13)
	v_mfma_f32_32x32x16_bf16 v[82:97], v[202:205], v[98:101], v[82:97]
	s_waitcnt lgkmcnt(12)
	v_mfma_f32_32x32x16_bf16 v[66:81], v[206:209], v[98:101], v[66:81]
	v_add_u32_e32 v202, v188, v179
	ds_read_b128 v[202:205], v202 offset:40960
	v_add_u32_e32 v206, v188, v179
	ds_read_b128 v[206:209], v206 offset:45056
	s_waitcnt lgkmcnt(11)
	v_mfma_f32_32x32x16_bf16 v[82:97], v[210:213], v[218:221], v[82:97]
	v_mfma_f32_32x32x16_bf16 v[66:81], v[214:217], v[218:221], v[66:81]
	ds_read_b128 v[210:213], v159 offset:4096
	v_add_u32_e32 v214, v188, v181
	ds_read_b128 v[214:217], v214 offset:40960
	v_add_u32_e32 v218, v188, v181
	ds_read_b128 v[218:221], v218 offset:45056
	s_waitcnt lgkmcnt(11)
	v_mfma_f32_32x32x16_bf16 v[82:97], v[222:225], v[230:233], v[82:97]
	v_mfma_f32_32x32x16_bf16 v[66:81], v[226:229], v[230:233], v[66:81]
	ds_read_b128 v[222:225], v159 offset:5120
	v_add_u32_e32 v226, v188, v183
	ds_read_b128 v[226:229], v226 offset:40960
	v_add_u32_e32 v230, v188, v183
	ds_read_b128 v[230:233], v230 offset:45056
	s_waitcnt lgkmcnt(11)
	v_mfma_f32_32x32x16_bf16 v[82:97], v[194:197], v[234:237], v[82:97]
	v_mfma_f32_32x32x16_bf16 v[66:81], v[198:201], v[234:237], v[66:81]
	ds_read_b128 v[194:197], v159 offset:6144
	s_waitcnt lgkmcnt(9)
	v_mfma_f32_32x32x16_bf16 v[82:97], v[238:241], v[246:249], v[82:97]
	v_mfma_f32_32x32x16_bf16 v[66:81], v[242:245], v[246:249], v[66:81]
	s_waitcnt lgkmcnt(6)
	v_mfma_f32_32x32x16_bf16 v[82:97], v[202:205], v[210:213], v[82:97]
	v_mfma_f32_32x32x16_bf16 v[66:81], v[206:209], v[210:213], v[66:81]
	s_waitcnt lgkmcnt(3)
	v_mfma_f32_32x32x16_bf16 v[82:97], v[214:217], v[222:225], v[82:97]
	v_mfma_f32_32x32x16_bf16 v[66:81], v[218:221], v[222:225], v[66:81]
	s_waitcnt lgkmcnt(0)
	v_mfma_f32_32x32x16_bf16 v[82:97], v[226:229], v[194:197], v[82:97]
	v_mfma_f32_32x32x16_bf16 v[66:81], v[230:233], v[194:197], v[66:81]
	s_and_b64 vcc, exec, s[6:7]
	s_cbranch_vccnz .LBB0_668
	s_waitcnt vmcnt(0)

.LBB0_676:
	v_cndmask_b32_e64 v186, v118, v186, s[8:9]
	v_sub_f32_e32 v82, v82, v186
	v_sub_f32_e32 v83, v83, v186
	v_exp_f32_e32 v82, v82
	v_sub_f32_e32 v84, v84, v186
	v_exp_f32_e32 v83, v83
	v_sub_f32_e32 v85, v85, v186
	v_exp_f32_e32 v84, v84
	v_sub_f32_e32 v86, v86, v186
	v_exp_f32_e32 v85, v85
	v_sub_f32_e32 v87, v87, v186
	v_exp_f32_e32 v86, v86
	v_sub_f32_e32 v88, v88, v186
	v_exp_f32_e32 v87, v87
	v_sub_f32_e32 v89, v89, v186
	v_exp_f32_e32 v88, v88
	v_sub_f32_e32 v90, v90, v186
	v_exp_f32_e32 v89, v89
	v_sub_f32_e32 v91, v91, v186
	v_exp_f32_e32 v90, v90
	v_sub_f32_e32 v92, v92, v186
	v_exp_f32_e32 v91, v91
	v_sub_f32_e32 v93, v93, v186
	v_exp_f32_e32 v92, v92
	v_sub_f32_e32 v94, v94, v186
	v_exp_f32_e32 v93, v93
	v_sub_f32_e32 v95, v95, v186
	v_exp_f32_e32 v94, v94
	v_sub_f32_e32 v96, v96, v186
	v_exp_f32_e32 v95, v95
	v_sub_f32_e32 v97, v97, v186
	v_exp_f32_e32 v96, v96
	v_sub_f32_e32 v66, v66, v186
	v_exp_f32_e32 v97, v97
	v_sub_f32_e32 v67, v67, v186
	v_exp_f32_e32 v66, v66
	v_sub_f32_e32 v68, v68, v186
	v_exp_f32_e32 v67, v67
	v_sub_f32_e32 v69, v69, v186
	v_exp_f32_e32 v68, v68
	v_sub_f32_e32 v70, v70, v186
	v_exp_f32_e32 v69, v69
	v_sub_f32_e32 v71, v71, v186
	v_exp_f32_e32 v70, v70
	v_sub_f32_e32 v72, v72, v186
	v_exp_f32_e32 v71, v71
	v_sub_f32_e32 v73, v73, v186
	v_exp_f32_e32 v72, v72
	v_sub_f32_e32 v74, v74, v186
	v_exp_f32_e32 v73, v73
	v_sub_f32_e32 v75, v75, v186
	v_exp_f32_e32 v74, v74
	v_sub_f32_e32 v76, v76, v186
	v_exp_f32_e32 v75, v75
	v_sub_f32_e32 v77, v77, v186
	v_exp_f32_e32 v76, v76
	v_sub_f32_e32 v78, v78, v186
	v_exp_f32_e32 v77, v77
	v_sub_f32_e32 v79, v79, v186
	v_exp_f32_e32 v78, v78
	v_sub_f32_e32 v80, v80, v186
	v_exp_f32_e32 v79, v79
	v_sub_f32_e32 v81, v81, v186
	v_exp_f32_e32 v80, v80
	v_exp_f32_e32 v81, v81
	s_and_b64 vcc, exec, s[2:3]
	v_cvt_pk_bf16_f32 v130, v82, v83
	v_cvt_pk_bf16_f32 v131, v84, v85
	v_cvt_pk_bf16_f32 v132, v86, v87
	v_cvt_pk_bf16_f32 v133, v88, v89
	v_cvt_pk_bf16_f32 v126, v90, v91
	v_cvt_pk_bf16_f32 v127, v92, v93
	v_cvt_pk_bf16_f32 v128, v94, v95
	v_cvt_pk_bf16_f32 v129, v96, v97
	v_cvt_pk_bf16_f32 v122, v66, v67
	v_cvt_pk_bf16_f32 v123, v68, v69
	v_cvt_pk_bf16_f32 v124, v70, v71
	v_cvt_pk_bf16_f32 v125, v72, v73
	v_cvt_pk_bf16_f32 v118, v74, v75
	v_cvt_pk_bf16_f32 v119, v76, v77
	v_cvt_pk_bf16_f32 v120, v78, v79
	v_cvt_pk_bf16_f32 v121, v80, v81
	s_cbranch_vccnz .LBB0_678
	s_waitcnt vmcnt(0)
.LBB0_678:
	s_barrier
	s_setprio 3
	v_add_u32_e32 v252, s12, v185
	ds_read_b64_tr_b16 v[204:205], v252 offset:0
	ds_read_b64_tr_b16 v[206:207], v252 offset:0x800
	ds_read_b64_tr_b16 v[208:209], v252 offset:0x1000
	ds_read_b64_tr_b16 v[210:211], v252 offset:0x1800
	ds_read_b64_tr_b16 v[212:213], v252 offset:0x2000
	ds_read_b64_tr_b16 v[214:215], v252 offset:0x2800
	ds_read_b64_tr_b16 v[216:217], v252 offset:0x3000
	ds_read_b64_tr_b16 v[218:219], v252 offset:0x3800
	s_waitcnt lgkmcnt(6)
	v_mfma_f32_32x32x16_bf16 v[50:65], v[130:133], v[204:207], v[50:65]
	v_add_f32_e32 v254, v66, v67
	v_add_f32_e32 v254, v68, v254
	v_add_f32_e32 v254, v69, v254
	ds_read_b64_tr_b16 v[220:221], v252 offset:0x200
	ds_read_b64_tr_b16 v[222:223], v252 offset:0xa00
	s_waitcnt lgkmcnt(6)
	v_mfma_f32_32x32x16_bf16 v[50:65], v[126:129], v[208:211], v[50:65]
	v_add_f32_e32 v254, v70, v254
	v_add_f32_e32 v254, v71, v254
	v_add_f32_e32 v254, v72, v254
	ds_read_b64_tr_b16 v[224:225], v252 offset:0x1200
	ds_read_b64_tr_b16 v[226:227], v252 offset:0x1a00
	ds_read_b128 v[236:239], v163
	s_waitcnt lgkmcnt(7)
	v_mfma_f32_32x32x16_bf16 v[50:65], v[122:125], v[212:215], v[50:65]
	v_add_f32_e32 v254, v73, v254
	v_add_f32_e32 v254, v74, v254
	v_add_f32_e32 v254, v75, v254
	ds_read_b128 v[66:69], v161
	ds_read_b128 v[70:73], v161 offset:8192
	ds_read_b64_tr_b16 v[228:229], v252 offset:0x2200
	ds_read_b64_tr_b16 v[230:231], v252 offset:0x2a00
	s_waitcnt lgkmcnt(9)
	v_mfma_f32_32x32x16_bf16 v[50:65], v[118:121], v[216:219], v[50:65]
	v_add_f32_e32 v254, v76, v254
	v_add_f32_e32 v254, v77, v254
	v_add_f32_e32 v254, v78, v254
	ds_read_b64_tr_b16 v[232:233], v252 offset:0x3200
	ds_read_b64_tr_b16 v[234:235], v252 offset:0x3a00
	ds_read_b128 v[240:243], v163 offset:8192
	s_waitcnt lgkmcnt(10)
	v_mfma_f32_32x32x16_bf16 v[34:49], v[130:133], v[220:223], v[34:49]
	v_add_f32_e32 v254, v79, v254
	v_add_f32_e32 v254, v80, v254
	v_add_f32_e32 v254, v81, v254
	ds_read_b64_tr_b16 v[204:205], v252 offset:0x400
	ds_read_b64_tr_b16 v[206:207], v252 offset:0xc00
	s_waitcnt lgkmcnt(10)
	v_mfma_f32_32x32x16_bf16 v[34:49], v[126:129], v[224:227], v[34:49]
	v_add_f32_e32 v254, v82, v254
	v_add_f32_e32 v254, v83, v254
	v_add_f32_e32 v254, v84, v254
	ds_read_b64_tr_b16 v[208:209], v252 offset:0x1400
	ds_read_b64_tr_b16 v[210:211], v252 offset:0x1c00
	ds_read_b128 v[244:247], v165
	s_waitcnt lgkmcnt(8)
	v_mfma_f32_32x32x16_bf16 v[34:49], v[122:125], v[228:231], v[34:49]
	v_add_f32_e32 v254, v85, v254
	v_add_f32_e32 v254, v86, v254
	v_add_f32_e32 v254, v87, v254
	ds_read_b64_tr_b16 v[212:213], v252 offset:0x2400
	ds_read_b64_tr_b16 v[214:215], v252 offset:0x2c00
	s_waitcnt lgkmcnt(8)
	v_mfma_f32_32x32x16_bf16 v[34:49], v[118:121], v[232:235], v[34:49]
	v_add_f32_e32 v254, v88, v254
	v_add_f32_e32 v254, v89, v254
	v_add_f32_e32 v254, v90, v254
	ds_read_b64_tr_b16 v[216:217], v252 offset:0x3400
	ds_read_b64_tr_b16 v[218:219], v252 offset:0x3c00
	ds_read_b128 v[248:251], v165 offset:8192
	s_waitcnt lgkmcnt(8)
	v_mfma_f32_32x32x16_bf16 v[18:33], v[130:133], v[204:207], v[18:33]
	v_add_f32_e32 v254, v91, v254
	v_add_f32_e32 v254, v92, v254
	v_add_f32_e32 v254, v93, v254
	ds_read_b64_tr_b16 v[220:221], v252 offset:0x600
	ds_read_b64_tr_b16 v[222:223], v252 offset:0xe00
	s_waitcnt lgkmcnt(8)
	v_mfma_f32_32x32x16_bf16 v[18:33], v[126:129], v[208:211], v[18:33]
	v_add_f32_e32 v254, v94, v254
	v_add_f32_e32 v254, v95, v254
	v_add_f32_e32 v254, v96, v254
	ds_read_b64_tr_b16 v[224:225], v252 offset:0x1600
	ds_read_b64_tr_b16 v[226:227], v252 offset:0x1e00
	s_waitcnt lgkmcnt(7)
	v_mfma_f32_32x32x16_bf16 v[18:33], v[122:125], v[212:215], v[18:33]
	v_add_f32_e32 v254, v97, v254
	v_mov_b32_e32 v97, v254
	s_nop 1
	ds_read_b64_tr_b16 v[228:229], v252 offset:0x2600
	ds_read_b64_tr_b16 v[230:231], v252 offset:0x2e00
	s_waitcnt lgkmcnt(7)
	v_mfma_f32_32x32x16_bf16 v[18:33], v[118:121], v[216:219], v[18:33]
	v_permlane32_swap_b32_e32 v254, v97
	v_add_f32_e32 v254, v254, v97
	v_fma_f32 v151, v151, v201, v254
	ds_read_b64_tr_b16 v[232:233], v252 offset:0x3600
	ds_read_b64_tr_b16 v[234:235], v252 offset:0x3e00
	s_waitcnt lgkmcnt(6)
	v_mfma_f32_32x32x16_bf16 v[2:17], v[130:133], v[220:223], v[2:17]
	s_waitcnt lgkmcnt(4)
	v_mfma_f32_32x32x16_bf16 v[2:17], v[126:129], v[224:227], v[2:17]
	ds_read_b128 v[204:207], v167
	ds_read_b128 v[208:211], v167 offset:8192
	s_waitcnt lgkmcnt(4)
	v_mfma_f32_32x32x16_bf16 v[2:17], v[122:125], v[228:231], v[2:17]
	s_waitcnt lgkmcnt(2)
	v_mfma_f32_32x32x16_bf16 v[2:17], v[118:121], v[232:235], v[2:17]
	ds_read_b128 v[212:215], v169
	ds_read_b128 v[216:219], v169 offset:8192
	v_mfma_f32_32x32x16_bf16 v[82:97], v[66:69], v[114:117], 0
	v_mfma_f32_32x32x16_bf16 v[66:81], v[70:73], v[114:117], 0
	ds_read_b128 v[220:223], v171
	ds_read_b128 v[224:227], v171 offset:8192
	ds_read_b128 v[228:231], v159
	v_mfma_f32_32x32x16_bf16 v[82:97], v[236:239], v[110:113], v[82:97]
	v_mfma_f32_32x32x16_bf16 v[66:81], v[240:243], v[110:113], v[66:81]
	ds_read_b128 v[232:235], v173
	ds_read_b128 v[236:239], v173 offset:8192
	ds_read_b128 v[240:243], v159 offset:1024
	v_mfma_f32_32x32x16_bf16 v[82:97], v[244:247], v[106:109], v[82:97]
	v_mfma_f32_32x32x16_bf16 v[66:81], v[248:251], v[106:109], v[66:81]
	ds_read_b128 v[244:247], v175
	ds_read_b128 v[248:251], v175 offset:8192
	s_waitcnt lgkmcnt(11)
	v_mfma_f32_32x32x16_bf16 v[82:97], v[204:207], v[102:105], v[82:97]
	s_waitcnt lgkmcnt(10)
	v_mfma_f32_32x32x16_bf16 v[66:81], v[208:211], v[102:105], v[66:81]
	ds_read_b128 v[204:207], v159 offset:2048
	ds_read_b128 v[208:211], v178 offset:32768
	s_waitcnt lgkmcnt(11)
	v_mfma_f32_32x32x16_bf16 v[82:97], v[212:215], v[98:101], v[82:97]
	s_waitcnt lgkmcnt(10)
	v_mfma_f32_32x32x16_bf16 v[66:81], v[216:219], v[98:101], v[66:81]
	ds_read_b128 v[212:215], v178 offset:36864
	ds_read_b128 v[216:219], v159 offset:3072
	s_waitcnt lgkmcnt(9)
	v_mfma_f32_32x32x16_bf16 v[82:97], v[220:223], v[228:231], v[82:97]
	v_mfma_f32_32x32x16_bf16 v[66:81], v[224:227], v[228:231], v[66:81]
	ds_read_b128 v[220:223], v180 offset:32768
	ds_read_b128 v[224:227], v180 offset:36864
	ds_read_b128 v[228:231], v159 offset:4096
	s_waitcnt lgkmcnt(9)
	v_mfma_f32_32x32x16_bf16 v[82:97], v[232:235], v[240:243], v[82:97]
	v_mfma_f32_32x32x16_bf16 v[66:81], v[236:239], v[240:243], v[66:81]
	ds_read_b128 v[232:235], v182 offset:32768
	ds_read_b128 v[236:239], v182 offset:36864
	ds_read_b128 v[240:243], v159 offset:5120
	s_waitcnt lgkmcnt(9)
	v_mfma_f32_32x32x16_bf16 v[82:97], v[244:247], v[204:207], v[82:97]
	v_mfma_f32_32x32x16_bf16 v[66:81], v[248:251], v[204:207], v[66:81]
	ds_read_b128 v[244:247], v184 offset:32768
	ds_read_b128 v[248:251], v184 offset:36864
	ds_read_b128 v[204:207], v159 offset:6144
	s_waitcnt lgkmcnt(9)
	v_mfma_f32_32x32x16_bf16 v[82:97], v[208:211], v[216:219], v[82:97]
	v_mfma_f32_32x32x16_bf16 v[66:81], v[212:215], v[216:219], v[66:81]
	s_waitcnt lgkmcnt(6)
	v_mfma_f32_32x32x16_bf16 v[82:97], v[220:223], v[228:231], v[82:97]
	v_mfma_f32_32x32x16_bf16 v[66:81], v[224:227], v[228:231], v[66:81]
	s_waitcnt lgkmcnt(3)
	v_mfma_f32_32x32x16_bf16 v[82:97], v[232:235], v[240:243], v[82:97]
	v_mfma_f32_32x32x16_bf16 v[66:81], v[236:239], v[240:243], v[66:81]
	s_waitcnt lgkmcnt(0)
	v_mfma_f32_32x32x16_bf16 v[82:97], v[244:247], v[204:207], v[82:97]
	v_mfma_f32_32x32x16_bf16 v[66:81], v[248:251], v[204:207], v[66:81]
	s_and_b64 vcc, exec, s[6:7]
	s_cbranch_vccnz .LBB0_680
	s_waitcnt vmcnt(0)

.LBB0_688:
	v_cndmask_b32_e64 v186, v118, v186, s[8:9]
	v_sub_f32_e32 v82, v82, v186
	v_sub_f32_e32 v83, v83, v186
	v_exp_f32_e32 v82, v82
	v_sub_f32_e32 v84, v84, v186
	v_exp_f32_e32 v83, v83
	v_sub_f32_e32 v85, v85, v186
	v_exp_f32_e32 v84, v84
	v_sub_f32_e32 v86, v86, v186
	v_sub_f32_e32 v66, v66, v186
	v_exp_f32_e32 v85, v85
	v_sub_f32_e32 v87, v87, v186
	v_exp_f32_e32 v86, v86
	v_exp_f32_e32 v66, v66
	v_sub_f32_e32 v88, v88, v186
	v_exp_f32_e32 v87, v87
	v_sub_f32_e32 v89, v89, v186
	v_exp_f32_e32 v88, v88
	v_sub_f32_e32 v90, v90, v186
	v_exp_f32_e32 v89, v89
	v_sub_f32_e32 v91, v91, v186
	v_exp_f32_e32 v90, v90
	v_sub_f32_e32 v92, v92, v186
	v_exp_f32_e32 v91, v91
	v_sub_f32_e32 v93, v93, v186
	v_exp_f32_e32 v92, v92
	v_sub_f32_e32 v94, v94, v186
	v_exp_f32_e32 v93, v93
	v_sub_f32_e32 v95, v95, v186
	v_exp_f32_e32 v94, v94
	v_sub_f32_e32 v96, v96, v186
	v_exp_f32_e32 v95, v95
	v_sub_f32_e32 v97, v97, v186
	v_exp_f32_e32 v96, v96
	v_exp_f32_e32 v97, v97
	v_sub_f32_e32 v67, v67, v186
	v_sub_f32_e32 v68, v68, v186
	v_exp_f32_e32 v67, v67
	v_sub_f32_e32 v69, v69, v186
	v_exp_f32_e32 v68, v68
	v_sub_f32_e32 v70, v70, v186
	v_exp_f32_e32 v69, v69
	v_sub_f32_e32 v71, v71, v186
	v_exp_f32_e32 v70, v70
	v_sub_f32_e32 v72, v72, v186
	v_exp_f32_e32 v71, v71
	v_sub_f32_e32 v73, v73, v186
	v_exp_f32_e32 v72, v72
	v_sub_f32_e32 v74, v74, v186
	v_exp_f32_e32 v73, v73
	v_sub_f32_e32 v75, v75, v186
	v_exp_f32_e32 v74, v74
	v_sub_f32_e32 v76, v76, v186
	v_exp_f32_e32 v75, v75
	v_sub_f32_e32 v77, v77, v186
	v_exp_f32_e32 v76, v76
	v_sub_f32_e32 v78, v78, v186
	v_exp_f32_e32 v77, v77
	v_sub_f32_e32 v79, v79, v186
	v_exp_f32_e32 v78, v78
	v_sub_f32_e32 v80, v80, v186
	v_exp_f32_e32 v79, v79
	v_sub_f32_e32 v81, v81, v186
	v_exp_f32_e32 v80, v80
	v_exp_f32_e32 v81, v81
	s_and_b64 vcc, exec, s[2:3]
	v_cvt_pk_bf16_f32 v130, v82, v83
	v_cvt_pk_bf16_f32 v131, v84, v85
	v_cvt_pk_bf16_f32 v132, v86, v87
	v_cvt_pk_bf16_f32 v133, v88, v89
	v_cvt_pk_bf16_f32 v126, v90, v91
	v_cvt_pk_bf16_f32 v127, v92, v93
	v_cvt_pk_bf16_f32 v128, v94, v95
	v_cvt_pk_bf16_f32 v129, v96, v97
	v_cvt_pk_bf16_f32 v122, v66, v67
	v_cvt_pk_bf16_f32 v123, v68, v69
	v_cvt_pk_bf16_f32 v124, v70, v71
	v_cvt_pk_bf16_f32 v125, v72, v73
	v_cvt_pk_bf16_f32 v118, v74, v75
	v_cvt_pk_bf16_f32 v119, v76, v77
	v_cvt_pk_bf16_f32 v120, v78, v79
	v_cvt_pk_bf16_f32 v121, v80, v81
	s_cbranch_vccnz .LBB0_690
	s_waitcnt vmcnt(0)
.LBB0_690:
	v_mov_b32_e32 v255, v204
	s_add_i32 s93, s93, 2
	s_and_b64 vcc, exec, s[56:57]
	s_cbranch_vccnz .Lrot_mla_exit
	s_mov_b32 s8, s95
	s_mov_b32 s95, s12
	v_add_u32_e32 v189, v187, v160
	v_add_u32_e32 v190, v187, v162
	v_add_u32_e32 v191, v187, v164
	v_add_u32_e32 v192, v187, v166
	s_branch .LBB0_666
.Lrot_mla_exit:
	s_barrier
	v_add_f32_e32 v254, v66, v67
	v_add_f32_e32 v254, v68, v254
	v_add_f32_e32 v254, v69, v254
	v_add_f32_e32 v254, v70, v254
	v_add_f32_e32 v254, v71, v254
	v_add_f32_e32 v254, v72, v254
	v_add_f32_e32 v254, v73, v254
	v_add_f32_e32 v254, v74, v254
	v_add_f32_e32 v254, v75, v254
	v_add_f32_e32 v254, v76, v254
	v_add_f32_e32 v254, v77, v254
	v_add_f32_e32 v254, v78, v254
	v_add_f32_e32 v254, v79, v254
	v_add_f32_e32 v254, v80, v254
	v_add_f32_e32 v254, v81, v254
	v_add_f32_e32 v254, v82, v254
	v_add_f32_e32 v254, v83, v254
	v_add_f32_e32 v254, v84, v254
	v_add_f32_e32 v254, v85, v254
	v_add_f32_e32 v254, v86, v254
	v_add_f32_e32 v254, v87, v254
	v_add_f32_e32 v254, v88, v254
	v_add_f32_e32 v254, v89, v254
	v_add_f32_e32 v254, v90, v254
	v_add_f32_e32 v254, v91, v254
	v_add_f32_e32 v254, v92, v254
	v_add_f32_e32 v254, v93, v254
	v_add_f32_e32 v254, v94, v254
	v_add_f32_e32 v254, v95, v254
	v_add_f32_e32 v254, v96, v254
	v_add_f32_e32 v254, v97, v254
	v_mov_b32_e32 v97, v254
	s_nop 1
	v_permlane32_swap_b32_e32 v254, v97
	v_add_f32_e32 v254, v254, v97
	v_fma_f32 v151, v151, v255, v254

	.amdhsa_kernel _Z6mk_fwd4Args
		.amdhsa_group_segment_fixed_size 0
		.amdhsa_private_segment_fixed_size 0
		.amdhsa_kernarg_size 456
		.amdhsa_user_sgpr_count 2
		.amdhsa_user_sgpr_dispatch_ptr 0
		.amdhsa_user_sgpr_queue_ptr 0
		.amdhsa_user_sgpr_kernarg_segment_ptr 1
		.amdhsa_user_sgpr_dispatch_id 0
		.amdhsa_user_sgpr_kernarg_preload_length 0
		.amdhsa_user_sgpr_kernarg_preload_offset 0
		.amdhsa_user_sgpr_private_segment_size 0
		.amdhsa_uses_dynamic_stack 0
		.amdhsa_enable_private_segment 0
		.amdhsa_system_sgpr_workgroup_id_x 1
		.amdhsa_system_sgpr_workgroup_id_y 0
		.amdhsa_system_sgpr_workgroup_id_z 0
		.amdhsa_system_sgpr_workgroup_info 0
		.amdhsa_system_vgpr_workitem_id 2
		.amdhsa_next_free_vgpr 256
		.amdhsa_next_free_sgpr 102
		.amdhsa_accum_offset 256
		.amdhsa_reserve_vcc 1
		.amdhsa_float_round_mode_32 0
		.amdhsa_float_round_mode_16_64 0
		.amdhsa_float_denorm_mode_32 3
		.amdhsa_float_denorm_mode_16_64 3
		.amdhsa_dx10_clamp 1
		.amdhsa_ieee_mode 1
		.amdhsa_fp16_overflow 0
		.amdhsa_tg_split 0
		.amdhsa_exception_fp_ieee_invalid_op 0
		.amdhsa_exception_fp_denorm_src 0
		.amdhsa_exception_fp_ieee_div_zero 0
		.amdhsa_exception_fp_ieee_overflow 0
		.amdhsa_exception_fp_ieee_underflow 0
		.amdhsa_exception_fp_ieee_inexact 0
		.amdhsa_exception_int_div_zero 0
	.end_amdhsa_kernel

amdhsa.kernels:
  - .agpr_count:     0
    .args:
      - .offset:         0
        .size:           200
        .value_kind:     by_value
      - .offset:         200
        .size:           4
        .value_kind:     hidden_block_count_x
      - .offset:         204
        .size:           4
        .value_kind:     hidden_block_count_y
      - .offset:         208
        .size:           4
        .value_kind:     hidden_block_count_z
      - .offset:         212
        .size:           2
        .value_kind:     hidden_group_size_x
      - .offset:         214
        .size:           2
        .value_kind:     hidden_group_size_y
      - .offset:         216
        .size:           2
        .value_kind:     hidden_group_size_z
      - .offset:         218
        .size:           2
        .value_kind:     hidden_remainder_x
      - .offset:         220
        .size:           2
        .value_kind:     hidden_remainder_y
      - .offset:         222
        .size:           2
        .value_kind:     hidden_remainder_z
      - .offset:         240
        .size:           8
        .value_kind:     hidden_global_offset_x
      - .offset:         248
        .size:           8
        .value_kind:     hidden_global_offset_y
      - .offset:         256
        .size:           8
        .value_kind:     hidden_global_offset_z
      - .offset:         264
        .size:           2
        .value_kind:     hidden_grid_dims
      - .offset:         288
        .size:           8
        .value_kind:     hidden_multigrid_sync_arg
      - .offset:         320
        .size:           4
        .value_kind:     hidden_dynamic_lds_size
    .group_segment_fixed_size: 0
    .kernarg_segment_align: 8
    .kernarg_segment_size: 456
    .language:       OpenCL C
    .language_version:
      - 2
      - 0
    .max_flat_workgroup_size: 512
    .name:           _Z6mk_fwd4Args
    .private_segment_fixed_size: 0
    .sgpr_count:     108
    .sgpr_spill_count: 20
    .symbol:         _Z6mk_fwd4Args.kd
    .uniform_work_group_size: 1
    .uses_dynamic_stack: false
    .vgpr_count:     256
    .vgpr_spill_count: 0
    .wavefront_size: 64
